# baseline (speedup 1.0000x reference)
; #define LAS __attribute__((address_space(3)))
; template <int S> __device__ __forceinline__ void fsm_chunk(f32x16& c0, f32x16& c1, float& ps, bf16x8& pa0, bf16x8& pa1, bf16x8& pa2, bf16x8& pa3) {
;   if constexpr (S < 8) { c1[2 * S] = __builtin_amdgcn_exp2f(c1[2 * S]); c1[2 * S + 1] = __builtin_amdgcn_exp2f(c1[2 * S + 1]); ps += c0[2 * S]; ps += c0[2 * S + 1]; if constexpr (S > 0) { ps += c1[2 * S - 2]; ps += c1[2 * S - 1]; } asm volatile("" : "+v"(c1), "+v"(ps)); }
;   else if constexpr (S == 8) { ps += c1[14]; ps += c1[15]; PK4(c0, 0, pa0); asm volatile("" : "+v"(pa0), "+v"(ps)); }
;   else if constexpr (S == 9) { PK4(c0, 8, pa1); asm volatile("" : "+v"(pa1)); }
;   else if constexpr (S == 10) { PK4(c1, 0, pa2); asm volatile("" : "+v"(pa2)); }
;   else { PK4(c1, 8, pa3); asm volatile("" : "+v"(pa3)); }
; }
; __device__ __forceinline__ void qk_fsm(f32x16& n0, f32x16& n1, f32x16& c0, f32x16& c1, float alC, float& l_reg, bf16x8& pa0, bf16x8& pa1, bf16x8& pa2, bf16x8& pa3,
;                                        const LAS char* kl, const int (&kx)[4], const bf16x8* qr, const LAS char* qrl) {
;   float ps = 0.f;
;     ...
;   QSLOT(0) QSLOT(1) QSLOT(2) QSLOT(3) QSLOT(4) QSLOT(5) QSLOT(6) QSLOT(7) QSLOT(8) QSLOT(9) QSLOT(10) QSLOT(11)
;     ...
;   { auto rr = __builtin_amdgcn_permlane32_swap(__float_as_uint(ps), __float_as_uint(ps), false, false); ps = __uint_as_float(rr[0]) + __uint_as_float(rr[1]); }
;   l_reg = l_reg * alC + ps;
; }
.LBB0_1011:
	s_add_u32 s4, s12, s31
	s_addc_u32 s5, s13, s9
	s_add_u32 s4, s4, 0x1dd0c000
	s_addc_u32 s5, s5, 0
	s_add_u32 s6, s12, s90
	s_addc_u32 s7, s13, s91
	s_add_u32 s6, s6, 0x25504000
	s_addc_u32 s7, s7, 0
	s_waitcnt lgkmcnt(0)
	ds_read_b128 v[244:247], v186 offset:57600
	ds_read_b128 v[248:251], v187 offset:12544
	ds_read_b128 v[238:241], v215
	v_exp_f32_e32 v64, v64
	v_exp_f32_e32 v65, v65
	v_mfma_f32_32x32x16_bf16 v[112:127], v[230:233], v[128:131], 0
	v_add_f32_e32 v96, 0, v80
	v_add_f32_e32 v162, v81, v96
	s_add_i32 m0, s98, 0x8000
	v_mfma_f32_32x32x16_bf16 v[96:111], v[234:237], v[128:131], 0
	global_load_lds_dwordx4 v177, s[4:5]
	s_waitcnt lgkmcnt(0)
	ds_read_b128 v[230:233], v188 offset:57344
	ds_read_b128 v[234:237], v189 offset:12288
	v_add_f32_e32 v162, v82, v162
	v_add_f32_e32 v162, v83, v162
	v_add_f32_e32 v162, v64, v162
	v_mfma_f32_32x32x16_bf16 v[112:127], v[244:247], v[238:241], v[112:127]
	v_exp_f32_e32 v66, v66
	v_exp_f32_e32 v67, v67
	v_add_f32_e32 v162, v65, v162
	s_add_i32 m0, s98, 0xa000
	v_mfma_f32_32x32x16_bf16 v[96:111], v[248:251], v[238:241], v[96:111]
	global_load_lds_dwordx4 v178, s[4:5]
	s_waitcnt lgkmcnt(0)
	ds_read_b128 v[244:247], v188 offset:57600
	ds_read_b128 v[248:251], v189 offset:12544
	ds_read_b128 v[238:241], v215 offset:1024
	v_add_f32_e32 v162, v84, v162
	v_add_f32_e32 v162, v85, v162
	v_add_f32_e32 v162, v66, v162
	v_mfma_f32_32x32x16_bf16 v[112:127], v[230:233], v[132:135], v[112:127]
	v_exp_f32_e32 v68, v68
	v_exp_f32_e32 v69, v69
	v_add_f32_e32 v162, v67, v162
	s_add_i32 m0, s98, 0xc000
	v_mfma_f32_32x32x16_bf16 v[96:111], v[234:237], v[132:135], v[96:111]
	global_load_lds_dwordx4 v179, s[4:5]
	s_waitcnt lgkmcnt(0)
	ds_read_b128 v[230:233], v190 offset:57344
	ds_read_b128 v[234:237], v191 offset:12288
	v_add_f32_e32 v162, v86, v162
	v_add_f32_e32 v162, v87, v162
	v_add_f32_e32 v162, v68, v162
	v_mfma_f32_32x32x16_bf16 v[112:127], v[244:247], v[238:241], v[112:127]
	v_exp_f32_e32 v70, v70
	v_exp_f32_e32 v71, v71
	v_add_f32_e32 v162, v69, v162
	s_add_i32 m0, s98, 0x4000
	v_mfma_f32_32x32x16_bf16 v[96:111], v[248:251], v[238:241], v[96:111]
	global_load_lds_dwordx4 v180, s[6:7]
	s_waitcnt lgkmcnt(0)
	ds_read_b128 v[244:247], v190 offset:57600
	ds_read_b128 v[248:251], v191 offset:12544
	ds_read_b128 v[238:241], v215 offset:2048
	v_add_f32_e32 v162, v88, v162
	v_add_f32_e32 v162, v89, v162
	v_add_f32_e32 v162, v70, v162
	v_mfma_f32_32x32x16_bf16 v[112:127], v[230:233], v[136:139], v[112:127]
	v_exp_f32_e32 v72, v72
	v_exp_f32_e32 v73, v73
	v_add_f32_e32 v162, v71, v162
	s_add_i32 m0, s98, 0x6000
	v_mfma_f32_32x32x16_bf16 v[96:111], v[234:237], v[136:139], v[96:111]
	global_load_lds_dwordx4 v181, s[6:7]
	s_waitcnt lgkmcnt(0)
	ds_read_b128 v[230:233], v192 offset:57344
	ds_read_b128 v[234:237], v193 offset:12288
	v_add_f32_e32 v162, v90, v162
	v_add_f32_e32 v162, v91, v162
	v_add_f32_e32 v162, v72, v162
	v_mfma_f32_32x32x16_bf16 v[112:127], v[244:247], v[238:241], v[112:127]
	v_exp_f32_e32 v74, v74
	v_exp_f32_e32 v75, v75
	v_add_f32_e32 v162, v73, v162
	v_mfma_f32_32x32x16_bf16 v[96:111], v[248:251], v[238:241], v[96:111]
	s_waitcnt lgkmcnt(0)
	ds_read_b128 v[244:247], v192 offset:57600
	ds_read_b128 v[248:251], v193 offset:12544
	ds_read_b128 v[238:241], v215 offset:3072
	v_add_f32_e32 v162, v92, v162
	v_add_f32_e32 v162, v93, v162
	v_add_f32_e32 v162, v74, v162
	v_mfma_f32_32x32x16_bf16 v[112:127], v[230:233], v[156:159], v[112:127]
	v_exp_f32_e32 v76, v76
	v_exp_f32_e32 v77, v77
	v_add_f32_e32 v162, v75, v162
	v_mfma_f32_32x32x16_bf16 v[96:111], v[234:237], v[156:159], v[96:111]
	s_waitcnt lgkmcnt(0)
	ds_read_b128 v[230:233], v186 offset:57472
	ds_read_b128 v[234:237], v187 offset:12416
	v_add_f32_e32 v162, v94, v162
	v_add_f32_e32 v162, v95, v162
	v_add_f32_e32 v162, v76, v162
	v_mfma_f32_32x32x16_bf16 v[112:127], v[244:247], v[238:241], v[112:127]
	v_exp_f32_e32 v78, v78
	v_exp_f32_e32 v79, v79
	v_add_f32_e32 v162, v77, v162
	v_mfma_f32_32x32x16_bf16 v[96:111], v[248:251], v[238:241], v[96:111]
	s_waitcnt lgkmcnt(0)
	ds_read_b128 v[244:247], v188 offset:57472
	ds_read_b128 v[248:251], v189 offset:12416
	v_add_f32_e32 v162, v162, v78
	v_cvt_pk_bf16_f32 v80, v80, v81
	v_cvt_pk_bf16_f32 v81, v82, v83
	v_cvt_pk_bf16_f32 v82, v84, v85
	v_mfma_f32_32x32x16_bf16 v[112:127], v[230:233], v[152:155], v[112:127]
	v_cvt_pk_bf16_f32 v83, v86, v87
	v_add_f32_e32 v227, v79, v162
	v_permlane32_swap_b32_e32 v80, v82
	v_permlane32_swap_b32_e32 v81, v83
	v_mfma_f32_32x32x16_bf16 v[96:111], v[234:237], v[152:155], v[96:111]
	s_waitcnt lgkmcnt(0)
	ds_read_b128 v[230:233], v190 offset:57472
	ds_read_b128 v[234:237], v191 offset:12416
	v_cvt_pk_bf16_f32 v84, v88, v89
	v_cvt_pk_bf16_f32 v85, v90, v91
	v_cvt_pk_bf16_f32 v86, v92, v93
	v_mfma_f32_32x32x16_bf16 v[112:127], v[244:247], v[148:151], v[112:127]
	v_cvt_pk_bf16_f32 v87, v94, v95
	v_permlane32_swap_b32_e32 v84, v86
	v_mfma_f32_32x32x16_bf16 v[96:111], v[248:251], v[148:151], v[96:111]
	v_permlane32_swap_b32_e32 v85, v87
	s_waitcnt lgkmcnt(0)
	ds_read_b128 v[244:247], v192 offset:57472
	ds_read_b128 v[248:251], v193 offset:12416
	v_cvt_pk_bf16_f32 v64, v64, v65
	v_cvt_pk_bf16_f32 v65, v66, v67
	v_cvt_pk_bf16_f32 v66, v68, v69
	v_mfma_f32_32x32x16_bf16 v[112:127], v[230:233], v[144:147], v[112:127]
	v_cvt_pk_bf16_f32 v67, v70, v71
	v_permlane32_swap_b32_e32 v64, v66
	v_mfma_f32_32x32x16_bf16 v[96:111], v[234:237], v[144:147], v[96:111]
	v_permlane32_swap_b32_e32 v65, v67
	s_waitcnt lgkmcnt(0)
; #define LAS __attribute__((address_space(3)))
; __device__ __forceinline__ float fma_s(float a, float b, float c) { float d; asm volatile("v_fma_f32 %0, %1, %2, %3" : "=v"(d) : "v"(a), "v"(b), "v"(c)); return d; }
; template <int S> __device__ __forceinline__ void psm_chunk(f32x16& p0, f32x16& p1, float& mx, float& m_reg, float& alpha, float& mnC) {
;   constexpr float C = SCALE * 1.4426950408889634f; const float Cv = C;
;   if constexpr (S == 0) { mx = p0[0];
; #pragma unroll
;     for (int r = 1; r < 16; ++r) mx = fmaxf(mx, p0[r]); }
;   else if constexpr (S == 1) {
; #pragma unroll
;     for (int r = 0; r < 16; ++r) mx = fmaxf(mx, p1[r]);
;     { auto rr = __builtin_amdgcn_permlane32_swap(__float_as_uint(mx), __float_as_uint(mx), false, false); mx = fmaxf(__uint_as_float(rr[0]), __uint_as_float(rr[1])); }
;     const float mn = (mx - m_reg > THR / SCALE) ? fmaxf(m_reg, mx) : m_reg; alpha = __builtin_amdgcn_exp2f((m_reg - mn) * C); m_reg = mn; mnC = -mn * C; }
;   else if constexpr (S == 2) {
; #pragma unroll
;     for (int r = 0; r < 8; ++r) p0[r] = fma_s(p0[r], Cv, mnC); }
;   else if constexpr (S == 3) {
; #pragma unroll
;     for (int r = 8; r < 16; ++r) p0[r] = fma_s(p0[r], Cv, mnC);
; #pragma unroll
;     for (int r = 0; r < 4; ++r) p0[r] = __builtin_amdgcn_exp2f(p0[r]); }
;   else if constexpr (S == 4) {
; #pragma unroll
;     for (int r = 0; r < 8; ++r) p1[r] = fma_s(p1[r], Cv, mnC);
; #pragma unroll
;     for (int r = 4; r < 8; ++r) p0[r] = __builtin_amdgcn_exp2f(p0[r]); }
;   else if constexpr (S == 5) {
; #pragma unroll
;     for (int r = 8; r < 16; ++r) p1[r] = fma_s(p1[r], Cv, mnC);
; #pragma unroll
;     for (int r = 8; r < 12; ++r) p0[r] = __builtin_amdgcn_exp2f(p0[r]); }
;   else if constexpr (S == 6) {
; #pragma unroll
;     for (int r = 12; r < 16; ++r) p0[r] = __builtin_amdgcn_exp2f(p0[r]); }
;   if constexpr (S == 0 || S == 1) asm volatile("" : "+v"(mx), "+v"(alpha), "+v"(mnC), "+v"(m_reg));
;   else if constexpr (S < 7) asm volatile("" : "+v"(p0), "+v"(p1));
; }
; __device__ __forceinline__ void pv_psm(f32x16* o, const LAS char* vl, bf16x8 pa0, bf16x8 pa1, bf16x8 pa2, bf16x8 pa3, f32x16& n0, f32x16& n1, float& m_reg, float& alN) {
;   float mx = 0.f, mnC = 0.f;
;     ...
;   VSLOT(0) VSLOT(1) VSLOT(2) VSLOT(3) VSLOT(4) VSLOT(5) VSLOT(6) VSLOT(7)
	ds_read_b64_tr_b16 v[234:235], v184
	ds_read_b64_tr_b16 v[236:237], v184 offset:2048
	ds_read_b64_tr_b16 v[238:239], v184 offset:4096
	ds_read_b64_tr_b16 v[240:241], v184 offset:6144
	v_cvt_pk_bf16_f32 v68, v72, v73
	v_cvt_pk_bf16_f32 v69, v74, v75
	v_cvt_pk_bf16_f32 v70, v76, v77
	v_mfma_f32_32x32x16_bf16 v[112:127], v[244:247], v[140:143], v[112:127]
	v_cvt_pk_bf16_f32 v71, v78, v79
	v_permlane32_swap_b32_e32 v68, v70
	v_mfma_f32_32x32x16_bf16 v[96:111], v[248:251], v[140:143], v[96:111]
	v_permlane32_swap_b32_e32 v69, v71
	v_mov_b32_e32 v229, v227
	s_nop 1
	v_permlane32_swap_b32_e32 v227, v229
	s_waitcnt lgkmcnt(0)
	ds_read_b64_tr_b16 v[72:73], v184 offset:8192
	ds_read_b64_tr_b16 v[74:75], v184 offset:10240
	ds_read_b64_tr_b16 v[76:77], v184 offset:12288
	ds_read_b64_tr_b16 v[78:79], v184 offset:14336
	v_max_f32_e32 v88, v113, v113
	v_max_f32_e32 v89, v112, v112
	v_mfma_f32_32x32x16_bf16 v[0:15], v[80:83], v[234:237], v[0:15]
	v_max_f32_e32 v88, v89, v88
	v_max3_f32 v88, v88, v114, v115
	v_max3_f32 v88, v88, v116, v117
	v_max3_f32 v252, v88, v118, v119
	v_max3_f32 v252, v252, v120, v121
	v_max3_f32 v252, v252, v122, v123
	v_max3_f32 v252, v252, v124, v125
	v_mfma_f32_32x32x16_bf16 v[0:15], v[84:87], v[238:241], v[0:15]
	v_max3_f32 v88, v252, v126, v127
	s_waitcnt lgkmcnt(0)
	ds_read_b64_tr_b16 v[234:235], v184 offset:512
	ds_read_b64_tr_b16 v[236:237], v184 offset:2560
	ds_read_b64_tr_b16 v[238:239], v184 offset:4608
	ds_read_b64_tr_b16 v[240:241], v184 offset:6656
	v_max3_f32 v88, v88, v96, v97
	v_max3_f32 v88, v88, v98, v99
	v_max3_f32 v88, v88, v100, v101
	v_max3_f32 v88, v88, v102, v103
	v_mfma_f32_32x32x16_bf16 v[0:15], v[64:67], v[72:75], v[0:15]
	v_max3_f32 v88, v88, v104, v105
	v_max3_f32 v88, v88, v106, v107
	v_max3_f32 v88, v88, v108, v109
	v_max3_f32 v88, v88, v110, v111
	v_mov_b32_e32 v89, v88
	s_nop 1
	v_permlane32_swap_b32_e32 v88, v89
	v_max_f32_e32 v89, v89, v89
	v_max_f32_e32 v88, v88, v88
	v_max_f32_e32 v88, v88, v89
	v_mfma_f32_32x32x16_bf16 v[0:15], v[68:71], v[76:79], v[0:15]
	v_sub_f32_e32 v89, v88, v228
	v_cmp_lt_f32_e32 vcc, s29, v89
	v_max_f32_e32 v89, v228, v228
	v_max_f32_e32 v89, v89, v88
	v_cndmask_b32_e32 v230, v228, v89, vcc
	v_sub_f32_e32 v89, v228, v230
	v_mul_f32_e32 v89, 0x3dd53b94, v89
	v_exp_f32_e32 v223, v89
	v_mul_f32_e32 v89, 0xbdd53b94, v230
	s_waitcnt lgkmcnt(0)
	ds_read_b64_tr_b16 v[72:73], v184 offset:8704
	ds_read_b64_tr_b16 v[74:75], v184 offset:10752
	ds_read_b64_tr_b16 v[76:77], v184 offset:12800
	ds_read_b64_tr_b16 v[78:79], v184 offset:14848
	v_fma_f32 v112, v112, v211, v89
	v_fma_f32 v113, v113, v211, v89
	v_mfma_f32_32x32x16_bf16 v[48:63], v[80:83], v[234:237], v[48:63]
	v_fma_f32 v114, v114, v211, v89
	v_fma_f32 v115, v115, v211, v89
	v_fma_f32 v116, v116, v211, v89
	v_fma_f32 v117, v117, v211, v89
	v_fma_f32 v118, v118, v211, v89
	v_fma_f32 v119, v119, v211, v89
	v_mfma_f32_32x32x16_bf16 v[48:63], v[84:87], v[238:241], v[48:63]
	s_waitcnt lgkmcnt(0)
	ds_read_b64_tr_b16 v[234:235], v184 offset:1024
	ds_read_b64_tr_b16 v[236:237], v184 offset:3072
	ds_read_b64_tr_b16 v[238:239], v184 offset:5120
	ds_read_b64_tr_b16 v[240:241], v184 offset:7168
	v_fma_f32 v120, v120, v211, v89
	v_fma_f32 v121, v121, v211, v89
	v_mfma_f32_32x32x16_bf16 v[48:63], v[64:67], v[72:75], v[48:63]
	v_fma_f32 v122, v122, v211, v89
	v_fma_f32 v123, v123, v211, v89
	v_fma_f32 v124, v124, v211, v89
	v_exp_f32_e32 v112, v112
	v_exp_f32_e32 v113, v113
	v_exp_f32_e32 v114, v114
	v_exp_f32_e32 v115, v115
	v_mfma_f32_32x32x16_bf16 v[48:63], v[68:71], v[76:79], v[48:63]
	v_fma_f32 v125, v125, v211, v89
	v_fma_f32 v126, v126, v211, v89
	v_fma_f32 v127, v127, v211, v89
	s_nop 0
	s_waitcnt lgkmcnt(0)
	ds_read_b64_tr_b16 v[72:73], v184 offset:9216
	ds_read_b64_tr_b16 v[74:75], v184 offset:11264
	ds_read_b64_tr_b16 v[76:77], v184 offset:13312
	ds_read_b64_tr_b16 v[78:79], v184 offset:15360
	v_fma_f32 v96, v96, v211, v89
	v_fma_f32 v97, v97, v211, v89
	v_mfma_f32_32x32x16_bf16 v[32:47], v[80:83], v[234:237], v[32:47]
	v_fma_f32 v98, v98, v211, v89
	v_fma_f32 v99, v99, v211, v89
	v_fma_f32 v100, v100, v211, v89
	v_exp_f32_e32 v116, v116
	v_exp_f32_e32 v117, v117
	v_exp_f32_e32 v118, v118
	v_exp_f32_e32 v119, v119
	v_mfma_f32_32x32x16_bf16 v[32:47], v[84:87], v[238:241], v[32:47]
	v_fma_f32 v101, v101, v211, v89
	v_fma_f32 v102, v102, v211, v89
	v_fma_f32 v103, v103, v211, v89
	s_nop 0
	s_waitcnt lgkmcnt(0)
	ds_read_b64_tr_b16 v[234:235], v184 offset:1536
	ds_read_b64_tr_b16 v[236:237], v184 offset:3584
	ds_read_b64_tr_b16 v[238:239], v184 offset:5632
	ds_read_b64_tr_b16 v[240:241], v184 offset:7680
	ds_read_b64_tr_b16 v[244:245], v184 offset:9728
	ds_read_b64_tr_b16 v[246:247], v184 offset:11776
	ds_read_b64_tr_b16 v[248:249], v184 offset:13824
	ds_read_b64_tr_b16 v[250:251], v184 offset:15872
	v_fma_f32 v104, v104, v211, v89
	v_fma_f32 v105, v105, v211, v89
	v_mfma_f32_32x32x16_bf16 v[32:47], v[64:67], v[72:75], v[32:47]
	v_fma_f32 v106, v106, v211, v89
	v_fma_f32 v107, v107, v211, v89
	v_fma_f32 v108, v108, v211, v89
	v_exp_f32_e32 v120, v120
	v_exp_f32_e32 v121, v121
	v_exp_f32_e32 v122, v122
	v_exp_f32_e32 v123, v123
	v_mfma_f32_32x32x16_bf16 v[32:47], v[68:71], v[76:79], v[32:47]
	v_fma_f32 v109, v109, v211, v89
	v_fma_f32 v110, v110, v211, v89
	v_fma_f32 v111, v111, v211, v89
	s_nop 0
	s_waitcnt lgkmcnt(0)
	v_mfma_f32_32x32x16_bf16 v[16:31], v[80:83], v[234:237], v[16:31]
	v_mfma_f32_32x32x16_bf16 v[16:31], v[84:87], v[238:241], v[16:31]
	s_waitcnt lgkmcnt(0)
	v_cmp_gt_f32_e32 vcc, 1.0, v223
	s_waitcnt vmcnt(0) lgkmcnt(0)
	s_barrier
; #define LAS __attribute__((address_space(3)))
; __device__ __forceinline__ float fma_s(float a, float b, float c) { float d; asm volatile("v_fma_f32 %0, %1, %2, %3" : "=v"(d) : "v"(a), "v"(b), "v"(c)); return d; }
; template <int S> __device__ __forceinline__ void psm_chunk(f32x16& p0, f32x16& p1, float& mx, float& m_reg, float& alpha, float& mnC) {
;   constexpr float C = SCALE * 1.4426950408889634f; const float Cv = C;
;   if constexpr (S == 0) { mx = p0[0];
; #pragma unroll
;     for (int r = 1; r < 16; ++r) mx = fmaxf(mx, p0[r]); }
;   else if constexpr (S == 1) {
; #pragma unroll
;     for (int r = 0; r < 16; ++r) mx = fmaxf(mx, p1[r]);
;     { auto rr = __builtin_amdgcn_permlane32_swap(__float_as_uint(mx), __float_as_uint(mx), false, false); mx = fmaxf(__uint_as_float(rr[0]), __uint_as_float(rr[1])); }
;     const float mn = (mx - m_reg > THR / SCALE) ? fmaxf(m_reg, mx) : m_reg; alpha = __builtin_amdgcn_exp2f((m_reg - mn) * C); m_reg = mn; mnC = -mn * C; }
;   else if constexpr (S == 2) {
; #pragma unroll
;     for (int r = 0; r < 8; ++r) p0[r] = fma_s(p0[r], Cv, mnC); }
;   else if constexpr (S == 3) {
; #pragma unroll
;     for (int r = 8; r < 16; ++r) p0[r] = fma_s(p0[r], Cv, mnC);
; #pragma unroll
;     for (int r = 0; r < 4; ++r) p0[r] = __builtin_amdgcn_exp2f(p0[r]); }
;   else if constexpr (S == 4) {
; #pragma unroll
;     for (int r = 0; r < 8; ++r) p1[r] = fma_s(p1[r], Cv, mnC);
; #pragma unroll
;     for (int r = 4; r < 8; ++r) p0[r] = __builtin_amdgcn_exp2f(p0[r]); }
;   else if constexpr (S == 5) {
; #pragma unroll
;     for (int r = 8; r < 16; ++r) p1[r] = fma_s(p1[r], Cv, mnC);
; #pragma unroll
;     for (int r = 8; r < 12; ++r) p0[r] = __builtin_amdgcn_exp2f(p0[r]); }
;   else if constexpr (S == 6) {
; #pragma unroll
;     for (int r = 12; r < 16; ++r) p0[r] = __builtin_amdgcn_exp2f(p0[r]); }
;   if constexpr (S == 0 || S == 1) asm volatile("" : "+v"(mx), "+v"(alpha), "+v"(mnC), "+v"(m_reg));
;   else if constexpr (S < 7) asm volatile("" : "+v"(p0), "+v"(p1));
; }
; __device__ __forceinline__ void pv_psm(f32x16* o, const LAS char* vl, bf16x8 pa0, bf16x8 pa1, bf16x8 pa2, bf16x8 pa3, f32x16& n0, f32x16& n1, float& m_reg, float& alN) {
;   float mx = 0.f, mnC = 0.f;
;     ...
;   VSLOT(0) VSLOT(1) VSLOT(2) VSLOT(3) VSLOT(4) VSLOT(5) VSLOT(6) VSLOT(7)
	ds_read_b128 v[232:235], v186 offset:32768
	ds_read_b128 v[236:239], v186 offset:45056
	v_mfma_f32_32x32x16_bf16 v[16:31], v[64:67], v[244:247], v[16:31]
	v_mfma_f32_32x32x16_bf16 v[16:31], v[68:71], v[248:251], v[16:31]
	v_exp_f32_e32 v124, v124
	v_exp_f32_e32 v125, v125
	v_exp_f32_e32 v126, v126
	v_exp_f32_e32 v127, v127
	s_cbranch_vccz .LBB0_1015
	s_and_saveexec_b64 s[6:7], s[40:41]
	ds_write_b32 v185, v223 offset:128
	s_or_b64 exec, exec, s[6:7]
	s_waitcnt lgkmcnt(0)
	ds_read_b128 v[64:67], v196 offset:224
	ds_read_b128 v[68:71], v196 offset:192
	ds_read_b128 v[72:75], v196 offset:160
	ds_read_b128 v[76:79], v196 offset:128
	s_waitcnt lgkmcnt(0)
	v_pk_mul_f32 v[12:13], v[12:13], v[64:65]
	v_pk_mul_f32 v[8:9], v[8:9], v[68:69]
	v_pk_mul_f32 v[4:5], v[4:5], v[72:73]
	v_pk_mul_f32 v[14:15], v[14:15], v[66:67]
	v_pk_mul_f32 v[10:11], v[10:11], v[70:71]
	v_pk_mul_f32 v[6:7], v[6:7], v[74:75]
	v_pk_mul_f32 v[2:3], v[2:3], v[78:79]
	v_pk_mul_f32 v[0:1], v[0:1], v[76:77]
	v_pk_mul_f32 v[60:61], v[60:61], v[64:65]
	v_pk_mul_f32 v[56:57], v[56:57], v[68:69]
	v_pk_mul_f32 v[52:53], v[52:53], v[72:73]
	v_pk_mul_f32 v[62:63], v[62:63], v[66:67]
	v_pk_mul_f32 v[58:59], v[58:59], v[70:71]
	v_pk_mul_f32 v[54:55], v[54:55], v[74:75]
	v_pk_mul_f32 v[50:51], v[50:51], v[78:79]
	v_pk_mul_f32 v[48:49], v[48:49], v[76:77]
	v_pk_mul_f32 v[44:45], v[44:45], v[64:65]
	v_pk_mul_f32 v[40:41], v[40:41], v[68:69]
	v_pk_mul_f32 v[36:37], v[36:37], v[72:73]
	v_pk_mul_f32 v[46:47], v[46:47], v[66:67]
	v_pk_mul_f32 v[42:43], v[42:43], v[70:71]
	v_pk_mul_f32 v[38:39], v[38:39], v[74:75]
	v_pk_mul_f32 v[34:35], v[34:35], v[78:79]
	v_pk_mul_f32 v[32:33], v[32:33], v[76:77]
	v_pk_mul_f32 v[28:29], v[28:29], v[64:65]
	v_pk_mul_f32 v[24:25], v[24:25], v[68:69]
	v_pk_mul_f32 v[20:21], v[20:21], v[72:73]
	v_pk_mul_f32 v[30:31], v[30:31], v[66:67]
	v_pk_mul_f32 v[26:27], v[26:27], v[70:71]
	v_pk_mul_f32 v[22:23], v[22:23], v[74:75]
	v_pk_mul_f32 v[18:19], v[18:19], v[78:79]
	v_pk_mul_f32 v[16:17], v[16:17], v[76:77]
.LBB0_1015:
	s_add_u32 s4, s12, s31
	s_addc_u32 s5, s13, s9
	s_add_u32 s4, s4, 0x1dd12000
	s_addc_u32 s5, s5, 0
	s_add_u32 s6, s12, s90
	s_addc_u32 s7, s13, s91
	s_add_u32 s6, s6, 0x25508000
	s_addc_u32 s7, s7, 0
	s_waitcnt lgkmcnt(0)
	ds_read_b128 v[244:247], v186 offset:33024
	ds_read_b128 v[248:251], v186 offset:45312
	ds_read_b128 v[240:243], v215
	v_exp_f32_e32 v96, v96
	v_exp_f32_e32 v97, v97
	v_mfma_f32_32x32x16_bf16 v[80:95], v[232:235], v[128:131], 0
	v_add_f32_e32 v64, 0, v112
	v_add_f32_e32 v162, v113, v64
	s_add_i32 m0, s98, 0xe000
	v_mfma_f32_32x32x16_bf16 v[64:79], v[236:239], v[128:131], 0
	global_load_lds_dwordx4 v177, s[4:5]
	s_waitcnt lgkmcnt(0)
	ds_read_b128 v[232:235], v188 offset:32768
	ds_read_b128 v[236:239], v188 offset:45056
	v_add_f32_e32 v162, v114, v162
	v_add_f32_e32 v162, v115, v162
	v_add_f32_e32 v162, v96, v162
	v_mfma_f32_32x32x16_bf16 v[80:95], v[244:247], v[240:243], v[80:95]
	v_exp_f32_e32 v98, v98
	v_exp_f32_e32 v99, v99
	v_add_f32_e32 v162, v97, v162
	s_add_i32 m0, s98, 0x10000
	v_mfma_f32_32x32x16_bf16 v[64:79], v[248:251], v[240:243], v[64:79]
	global_load_lds_dwordx4 v178, s[4:5]
	s_waitcnt lgkmcnt(0)
	ds_read_b128 v[244:247], v188 offset:33024
	ds_read_b128 v[248:251], v188 offset:45312
	ds_read_b128 v[240:243], v215 offset:1024
	v_add_f32_e32 v162, v116, v162
	v_add_f32_e32 v162, v117, v162
	v_add_f32_e32 v162, v98, v162
	v_mfma_f32_32x32x16_bf16 v[80:95], v[232:235], v[132:135], v[80:95]
	v_exp_f32_e32 v100, v100
	v_exp_f32_e32 v101, v101
	v_add_f32_e32 v162, v99, v162
	s_add_i32 m0, s98, 0x12000
	v_mfma_f32_32x32x16_bf16 v[64:79], v[236:239], v[132:135], v[64:79]
	global_load_lds_dwordx4 v179, s[4:5]
	s_waitcnt lgkmcnt(0)
	ds_read_b128 v[232:235], v190 offset:32768
	ds_read_b128 v[236:239], v190 offset:45056
	v_add_f32_e32 v162, v118, v162
	v_add_f32_e32 v162, v119, v162
	v_add_f32_e32 v162, v100, v162
	v_mfma_f32_32x32x16_bf16 v[80:95], v[244:247], v[240:243], v[80:95]
	v_exp_f32_e32 v102, v102
	v_exp_f32_e32 v103, v103
	v_add_f32_e32 v162, v101, v162
	s_mov_b32 m0, s98
	v_mfma_f32_32x32x16_bf16 v[64:79], v[248:251], v[240:243], v[64:79]
	global_load_lds_dwordx4 v180, s[6:7]
	s_waitcnt lgkmcnt(0)
	ds_read_b128 v[244:247], v190 offset:33024
	ds_read_b128 v[248:251], v190 offset:45312
	ds_read_b128 v[240:243], v215 offset:2048
	v_add_f32_e32 v162, v120, v162
	v_add_f32_e32 v162, v121, v162
	v_add_f32_e32 v162, v102, v162
	v_mfma_f32_32x32x16_bf16 v[80:95], v[232:235], v[136:139], v[80:95]
	v_exp_f32_e32 v104, v104
	v_exp_f32_e32 v105, v105
	v_add_f32_e32 v162, v103, v162
	s_add_i32 m0, s98, 0x2000
	v_mfma_f32_32x32x16_bf16 v[64:79], v[236:239], v[136:139], v[64:79]
	global_load_lds_dwordx4 v181, s[6:7]
	s_waitcnt lgkmcnt(0)
	ds_read_b128 v[232:235], v192 offset:32768
	ds_read_b128 v[236:239], v192 offset:45056
	v_add_f32_e32 v162, v122, v162
	v_add_f32_e32 v162, v123, v162
	v_add_f32_e32 v162, v104, v162
	v_mfma_f32_32x32x16_bf16 v[80:95], v[244:247], v[240:243], v[80:95]
	v_exp_f32_e32 v106, v106
	v_exp_f32_e32 v107, v107
	v_add_f32_e32 v162, v105, v162
	v_mfma_f32_32x32x16_bf16 v[64:79], v[248:251], v[240:243], v[64:79]
	s_waitcnt lgkmcnt(0)
	ds_read_b128 v[244:247], v192 offset:33024
	ds_read_b128 v[248:251], v192 offset:45312
	ds_read_b128 v[240:243], v215 offset:3072
	v_add_f32_e32 v162, v124, v162
	v_add_f32_e32 v162, v125, v162
	v_add_f32_e32 v162, v106, v162
	v_mfma_f32_32x32x16_bf16 v[80:95], v[232:235], v[156:159], v[80:95]
	v_exp_f32_e32 v108, v108
	v_exp_f32_e32 v109, v109
	v_add_f32_e32 v162, v107, v162
	v_mfma_f32_32x32x16_bf16 v[64:79], v[236:239], v[156:159], v[64:79]
	s_waitcnt lgkmcnt(0)
; #define LAS __attribute__((address_space(3)))
; __device__ __forceinline__ void qk_fsm(f32x16& n0, f32x16& n1, f32x16& c0, f32x16& c1, float alC, float& l_reg, bf16x8& pa0, bf16x8& pa1, bf16x8& pa2, bf16x8& pa3,
;                                        const LAS char* kl, const int (&kx)[4], const bf16x8* qr, const LAS char* qrl) {
;   float ps = 0.f;
;     ...
;   QSLOT(0) QSLOT(1) QSLOT(2) QSLOT(3) QSLOT(4) QSLOT(5) QSLOT(6) QSLOT(7) QSLOT(8) QSLOT(9) QSLOT(10) QSLOT(11)
;     ...
;   { auto rr = __builtin_amdgcn_permlane32_swap(__float_as_uint(ps), __float_as_uint(ps), false, false); ps = __uint_as_float(rr[0]) + __uint_as_float(rr[1]); }
;   l_reg = l_reg * alC + ps;
; }
; template <int S> __device__ __forceinline__ void psm_chunk(f32x16& p0, f32x16& p1, float& mx, float& m_reg, float& alpha, float& mnC) {
;   constexpr float C = SCALE * 1.4426950408889634f; const float Cv = C;
;   if constexpr (S == 0) { mx = p0[0];
; #pragma unroll
;     for (int r = 1; r < 16; ++r) mx = fmaxf(mx, p0[r]); }
;   else if constexpr (S == 1) {
; #pragma unroll
;     for (int r = 0; r < 16; ++r) mx = fmaxf(mx, p1[r]);
;     { auto rr = __builtin_amdgcn_permlane32_swap(__float_as_uint(mx), __float_as_uint(mx), false, false); mx = fmaxf(__uint_as_float(rr[0]), __uint_as_float(rr[1])); }
;     const float mn = (mx - m_reg > THR / SCALE) ? fmaxf(m_reg, mx) : m_reg; alpha = __builtin_amdgcn_exp2f((m_reg - mn) * C); m_reg = mn; mnC = -mn * C; }
;   else if constexpr (S == 2) {
; #pragma unroll
;     for (int r = 0; r < 8; ++r) p0[r] = fma_s(p0[r], Cv, mnC); }
;   else if constexpr (S == 3) {
; #pragma unroll
;     for (int r = 8; r < 16; ++r) p0[r] = fma_s(p0[r], Cv, mnC);
; #pragma unroll
;     for (int r = 0; r < 4; ++r) p0[r] = __builtin_amdgcn_exp2f(p0[r]); }
;   else if constexpr (S == 4) {
; #pragma unroll
;     for (int r = 0; r < 8; ++r) p1[r] = fma_s(p1[r], Cv, mnC);
; #pragma unroll
;     for (int r = 4; r < 8; ++r) p0[r] = __builtin_amdgcn_exp2f(p0[r]); }
;   else if constexpr (S == 5) {
; #pragma unroll
;     for (int r = 8; r < 16; ++r) p1[r] = fma_s(p1[r], Cv, mnC);
; #pragma unroll
;     for (int r = 8; r < 12; ++r) p0[r] = __builtin_amdgcn_exp2f(p0[r]); }
;   else if constexpr (S == 6) {
; #pragma unroll
;     for (int r = 12; r < 16; ++r) p0[r] = __builtin_amdgcn_exp2f(p0[r]); }
;   if constexpr (S == 0 || S == 1) asm volatile("" : "+v"(mx), "+v"(alpha), "+v"(mnC), "+v"(m_reg));
	ds_read_b128 v[232:235], v186 offset:32896
	ds_read_b128 v[236:239], v186 offset:45184
	v_add_f32_e32 v162, v126, v162
	v_add_f32_e32 v162, v127, v162
	v_add_f32_e32 v162, v108, v162
	v_mfma_f32_32x32x16_bf16 v[80:95], v[244:247], v[240:243], v[80:95]
	v_exp_f32_e32 v110, v110
	v_exp_f32_e32 v111, v111
	v_add_f32_e32 v162, v109, v162
	v_mfma_f32_32x32x16_bf16 v[64:79], v[248:251], v[240:243], v[64:79]
	s_waitcnt lgkmcnt(0)
	ds_read_b128 v[244:247], v188 offset:32896
	ds_read_b128 v[248:251], v188 offset:45184
	v_add_f32_e32 v162, v162, v110
	v_cvt_pk_bf16_f32 v112, v112, v113
	v_cvt_pk_bf16_f32 v113, v114, v115
	v_cvt_pk_bf16_f32 v114, v116, v117
	v_mfma_f32_32x32x16_bf16 v[80:95], v[232:235], v[152:155], v[80:95]
	v_cvt_pk_bf16_f32 v115, v118, v119
	v_add_f32_e32 v231, v111, v162
	v_permlane32_swap_b32_e32 v112, v114
	v_permlane32_swap_b32_e32 v113, v115
	v_mfma_f32_32x32x16_bf16 v[64:79], v[236:239], v[152:155], v[64:79]
	s_waitcnt lgkmcnt(0)
	ds_read_b128 v[232:235], v190 offset:32896
	ds_read_b128 v[236:239], v190 offset:45184
	v_cvt_pk_bf16_f32 v116, v120, v121
	v_cvt_pk_bf16_f32 v117, v122, v123
	v_cvt_pk_bf16_f32 v118, v124, v125
	v_mfma_f32_32x32x16_bf16 v[80:95], v[244:247], v[148:151], v[80:95]
	v_cvt_pk_bf16_f32 v119, v126, v127
	v_permlane32_swap_b32_e32 v116, v118
	v_mfma_f32_32x32x16_bf16 v[64:79], v[248:251], v[148:151], v[64:79]
	v_permlane32_swap_b32_e32 v117, v119
	s_waitcnt lgkmcnt(0)
	ds_read_b128 v[244:247], v192 offset:32896
	ds_read_b128 v[248:251], v192 offset:45184
	v_cvt_pk_bf16_f32 v96, v96, v97
	v_cvt_pk_bf16_f32 v97, v98, v99
	v_cvt_pk_bf16_f32 v98, v100, v101
	v_mfma_f32_32x32x16_bf16 v[80:95], v[232:235], v[144:147], v[80:95]
	v_cvt_pk_bf16_f32 v99, v102, v103
	v_permlane32_swap_b32_e32 v96, v98
	v_mfma_f32_32x32x16_bf16 v[64:79], v[236:239], v[144:147], v[64:79]
	v_permlane32_swap_b32_e32 v97, v99
	s_waitcnt lgkmcnt(0)
	ds_read_b64_tr_b16 v[232:233], v184 offset:16384
	ds_read_b64_tr_b16 v[234:235], v184 offset:18432
	ds_read_b64_tr_b16 v[236:237], v184 offset:20480
	ds_read_b64_tr_b16 v[238:239], v184 offset:22528
	v_cvt_pk_bf16_f32 v100, v104, v105
	v_cvt_pk_bf16_f32 v101, v106, v107
	v_cvt_pk_bf16_f32 v102, v108, v109
	v_mfma_f32_32x32x16_bf16 v[80:95], v[244:247], v[140:143], v[80:95]
	v_cvt_pk_bf16_f32 v103, v110, v111
	v_permlane32_swap_b32_e32 v100, v102
	v_mfma_f32_32x32x16_bf16 v[64:79], v[248:251], v[140:143], v[64:79]
	v_permlane32_swap_b32_e32 v101, v103
	v_mov_b32_e32 v104, v231
	s_nop 1
	v_permlane32_swap_b32_e32 v231, v104
	s_waitcnt lgkmcnt(0)
	ds_read_b64_tr_b16 v[106:107], v184 offset:24576
	ds_read_b64_tr_b16 v[108:109], v184 offset:26624
	ds_read_b64_tr_b16 v[120:121], v184 offset:28672
	ds_read_b64_tr_b16 v[122:123], v184 offset:30720
	v_max_f32_e32 v105, v81, v81
	v_max_f32_e32 v110, v80, v80
	v_mfma_f32_32x32x16_bf16 v[0:15], v[112:115], v[232:235], v[0:15]
	v_max_f32_e32 v105, v110, v105
	v_max3_f32 v105, v105, v82, v83
	v_max3_f32 v105, v105, v84, v85
	v_max3_f32 v105, v105, v86, v87
	v_max3_f32 v105, v105, v88, v89
	v_max3_f32 v105, v105, v90, v91
	v_max3_f32 v105, v105, v92, v93
	v_mfma_f32_32x32x16_bf16 v[0:15], v[116:119], v[236:239], v[0:15]
	v_max3_f32 v105, v105, v94, v95
	s_waitcnt lgkmcnt(0)
	ds_read_b64_tr_b16 v[232:233], v184 offset:16896
	ds_read_b64_tr_b16 v[234:235], v184 offset:18944
	ds_read_b64_tr_b16 v[236:237], v184 offset:20992
	ds_read_b64_tr_b16 v[238:239], v184 offset:23040
	v_max3_f32 v105, v105, v64, v65
	v_max3_f32 v105, v105, v66, v67
	v_max3_f32 v105, v105, v68, v69
	v_max3_f32 v105, v105, v70, v71
	v_mfma_f32_32x32x16_bf16 v[0:15], v[96:99], v[106:109], v[0:15]
	v_max3_f32 v105, v105, v72, v73
	v_max3_f32 v105, v105, v74, v75
	v_max3_f32 v105, v105, v76, v77
	v_max3_f32 v105, v105, v78, v79
	v_mov_b32_e32 v110, v105
	s_nop 1
	v_permlane32_swap_b32_e32 v105, v110
	v_max_f32_e32 v110, v110, v110
	v_max_f32_e32 v105, v105, v105
	v_max_f32_e32 v105, v105, v110
	v_mfma_f32_32x32x16_bf16 v[0:15], v[100:103], v[120:123], v[0:15]
	v_sub_f32_e32 v110, v105, v230
	v_cmp_lt_f32_e32 vcc, s29, v110
	v_max_f32_e32 v110, v230, v230
	v_max_f32_e32 v110, v110, v105
	v_cndmask_b32_e32 v228, v230, v110, vcc
	v_sub_f32_e32 v110, v230, v228
	v_mul_f32_e32 v110, 0x3dd53b94, v110
	v_exp_f32_e32 v162, v110
	v_mul_f32_e32 v110, 0xbdd53b94, v228
	s_waitcnt lgkmcnt(0)
	ds_read_b64_tr_b16 v[106:107], v184 offset:25088
	ds_read_b64_tr_b16 v[108:109], v184 offset:27136
	ds_read_b64_tr_b16 v[120:121], v184 offset:29184
	ds_read_b64_tr_b16 v[122:123], v184 offset:31232
	v_fma_f32 v80, v80, v211, v110
	v_fma_f32 v81, v81, v211, v110
	v_mfma_f32_32x32x16_bf16 v[48:63], v[112:115], v[232:235], v[48:63]
	v_fma_f32 v82, v82, v211, v110
	v_fma_f32 v83, v83, v211, v110
	v_fma_f32 v84, v84, v211, v110
	v_fma_f32 v85, v85, v211, v110
	v_fma_f32 v86, v86, v211, v110
	v_fma_f32 v87, v87, v211, v110
	v_mfma_f32_32x32x16_bf16 v[48:63], v[116:119], v[236:239], v[48:63]
	s_waitcnt lgkmcnt(0)
; #define LAS __attribute__((address_space(3)))
; template <int S> __device__ __forceinline__ void psm_chunk(f32x16& p0, f32x16& p1, float& mx, float& m_reg, float& alpha, float& mnC) {
;   constexpr float C = SCALE * 1.4426950408889634f; const float Cv = C;
;   if constexpr (S == 0) { mx = p0[0];
; #pragma unroll
;     for (int r = 1; r < 16; ++r) mx = fmaxf(mx, p0[r]); }
;   else if constexpr (S == 1) {
; #pragma unroll
;     for (int r = 0; r < 16; ++r) mx = fmaxf(mx, p1[r]);
;     { auto rr = __builtin_amdgcn_permlane32_swap(__float_as_uint(mx), __float_as_uint(mx), false, false); mx = fmaxf(__uint_as_float(rr[0]), __uint_as_float(rr[1])); }
;     const float mn = (mx - m_reg > THR / SCALE) ? fmaxf(m_reg, mx) : m_reg; alpha = __builtin_amdgcn_exp2f((m_reg - mn) * C); m_reg = mn; mnC = -mn * C; }
;   else if constexpr (S == 2) {
; #pragma unroll
;     for (int r = 0; r < 8; ++r) p0[r] = fma_s(p0[r], Cv, mnC); }
;   else if constexpr (S == 3) {
; #pragma unroll
;     for (int r = 8; r < 16; ++r) p0[r] = fma_s(p0[r], Cv, mnC);
; #pragma unroll
;     for (int r = 0; r < 4; ++r) p0[r] = __builtin_amdgcn_exp2f(p0[r]); }
;   else if constexpr (S == 4) {
; #pragma unroll
;     for (int r = 0; r < 8; ++r) p1[r] = fma_s(p1[r], Cv, mnC);
; #pragma unroll
;     for (int r = 4; r < 8; ++r) p0[r] = __builtin_amdgcn_exp2f(p0[r]); }
;   else if constexpr (S == 5) {
; #pragma unroll
;     for (int r = 8; r < 16; ++r) p1[r] = fma_s(p1[r], Cv, mnC);
; #pragma unroll
;     for (int r = 8; r < 12; ++r) p0[r] = __builtin_amdgcn_exp2f(p0[r]); }
;   else if constexpr (S == 6) {
; #pragma unroll
;     for (int r = 12; r < 16; ++r) p0[r] = __builtin_amdgcn_exp2f(p0[r]); }
;   if constexpr (S == 0 || S == 1) asm volatile("" : "+v"(mx), "+v"(alpha), "+v"(mnC), "+v"(m_reg));
;   else if constexpr (S < 7) asm volatile("" : "+v"(p0), "+v"(p1));
; }
; __device__ __forceinline__ void pv_psm(f32x16* o, const LAS char* vl, bf16x8 pa0, bf16x8 pa1, bf16x8 pa2, bf16x8 pa3, f32x16& n0, f32x16& n1, float& m_reg, float& alN) {
;   float mx = 0.f, mnC = 0.f;
;     ...
;   VSLOT(0) VSLOT(1) VSLOT(2) VSLOT(3) VSLOT(4) VSLOT(5) VSLOT(6) VSLOT(7)
; __device__ __forceinline__ void attn_unit(const bf16_t* __restrict__ Qb, const bf16_t* __restrict__ Kh, const bf16_t* __restrict__ Vh, bf16_t* __restrict__ Ob, float* __restrict__ ssq, char* lds, LAS unsigned char* ldsl, ...
;     ...
;   constexpr int NT = SEQ / KVBLK;
	ds_read_b64_tr_b16 v[232:233], v184 offset:17408
	ds_read_b64_tr_b16 v[234:235], v184 offset:19456
	ds_read_b64_tr_b16 v[236:237], v184 offset:21504
	ds_read_b64_tr_b16 v[238:239], v184 offset:23552
	v_fma_f32 v88, v88, v211, v110
	v_fma_f32 v89, v89, v211, v110
	v_mfma_f32_32x32x16_bf16 v[48:63], v[96:99], v[106:109], v[48:63]
	v_fma_f32 v90, v90, v211, v110
	v_fma_f32 v91, v91, v211, v110
	v_fma_f32 v92, v92, v211, v110
	v_exp_f32_e32 v80, v80
	v_exp_f32_e32 v81, v81
	v_exp_f32_e32 v82, v82
	v_exp_f32_e32 v83, v83
	v_mfma_f32_32x32x16_bf16 v[48:63], v[100:103], v[120:123], v[48:63]
	v_fma_f32 v93, v93, v211, v110
	v_fma_f32 v94, v94, v211, v110
	v_fma_f32 v95, v95, v211, v110
	s_nop 0
	s_waitcnt lgkmcnt(0)
	ds_read_b64_tr_b16 v[106:107], v184 offset:25600
	ds_read_b64_tr_b16 v[108:109], v184 offset:27648
	ds_read_b64_tr_b16 v[120:121], v184 offset:29696
	ds_read_b64_tr_b16 v[122:123], v184 offset:31744
	v_fma_f32 v64, v64, v211, v110
	v_fma_f32 v65, v65, v211, v110
	v_mfma_f32_32x32x16_bf16 v[32:47], v[112:115], v[232:235], v[32:47]
	v_fma_f32 v66, v66, v211, v110
	v_fma_f32 v67, v67, v211, v110
	v_fma_f32 v68, v68, v211, v110
	v_exp_f32_e32 v84, v84
	v_exp_f32_e32 v85, v85
	v_exp_f32_e32 v86, v86
	v_exp_f32_e32 v87, v87
	v_mfma_f32_32x32x16_bf16 v[32:47], v[116:119], v[236:239], v[32:47]
	v_fma_f32 v69, v69, v211, v110
	v_fma_f32 v70, v70, v211, v110
	v_fma_f32 v71, v71, v211, v110
	s_nop 0
	s_waitcnt lgkmcnt(0)
	ds_read_b64_tr_b16 v[232:233], v184 offset:17920
	ds_read_b64_tr_b16 v[234:235], v184 offset:19968
	ds_read_b64_tr_b16 v[236:237], v184 offset:22016
	ds_read_b64_tr_b16 v[238:239], v184 offset:24064
	ds_read_b64_tr_b16 v[244:245], v184 offset:26112
	ds_read_b64_tr_b16 v[246:247], v184 offset:28160
	ds_read_b64_tr_b16 v[248:249], v184 offset:30208
	ds_read_b64_tr_b16 v[250:251], v184 offset:32256
	v_fma_f32 v72, v72, v211, v110
	v_fma_f32 v73, v73, v211, v110
	v_mfma_f32_32x32x16_bf16 v[32:47], v[96:99], v[106:109], v[32:47]
	v_fma_f32 v74, v74, v211, v110
	v_fma_f32 v75, v75, v211, v110
	v_fma_f32 v76, v76, v211, v110
	v_exp_f32_e32 v88, v88
	v_exp_f32_e32 v89, v89
	v_exp_f32_e32 v90, v90
	v_exp_f32_e32 v91, v91
	v_mfma_f32_32x32x16_bf16 v[32:47], v[100:103], v[120:123], v[32:47]
	v_fma_f32 v77, v77, v211, v110
	v_fma_f32 v78, v78, v211, v110
	v_fma_f32 v79, v79, v211, v110
	s_nop 0
	s_waitcnt lgkmcnt(0)
	v_mfma_f32_32x32x16_bf16 v[16:31], v[112:115], v[232:235], v[16:31]
	v_mfma_f32_32x32x16_bf16 v[16:31], v[116:119], v[236:239], v[16:31]
	s_waitcnt lgkmcnt(0)
	v_add_f32_e32 v252, v227, v229
	v_fmac_f32_e32 v252, v224, v171
	v_add_f32_e32 v171, v231, v104
	v_fmac_f32_e32 v171, v252, v223
	v_cmp_gt_f32_e32 vcc, 1.0, v162
	s_waitcnt vmcnt(0) lgkmcnt(0)
	s_barrier
	ds_read_b128 v[230:233], v186 offset:57344
	ds_read_b128 v[234:237], v187 offset:12288
	v_mfma_f32_32x32x16_bf16 v[16:31], v[96:99], v[244:247], v[16:31]
	v_mfma_f32_32x32x16_bf16 v[16:31], v[100:103], v[248:251], v[16:31]
	v_exp_f32_e32 v92, v92
	v_exp_f32_e32 v93, v93
	v_exp_f32_e32 v94, v94
	v_exp_f32_e32 v95, v95
	s_add_i32 s24, s24, 2
	s_add_u32 s31, s31, 0xc000
	s_addc_u32 s9, s9, 0
	s_add_u32 s90, s90, 0x8000
	s_addc_u32 s91, s91, 0
	s_cbranch_vccz .LBB0_1019
	s_and_saveexec_b64 s[6:7], s[40:41]
	ds_write_b32 v185, v162 offset:128
	s_or_b64 exec, exec, s[6:7]
	s_waitcnt lgkmcnt(0)
	ds_read_b128 v[96:99], v196 offset:224
	ds_read_b128 v[100:103], v196 offset:192
	ds_read_b128 v[106:109], v196 offset:160
	ds_read_b128 v[110:113], v196 offset:128
	s_waitcnt lgkmcnt(0)
	v_pk_mul_f32 v[12:13], v[12:13], v[96:97]
	v_pk_mul_f32 v[8:9], v[8:9], v[100:101]
	v_pk_mul_f32 v[4:5], v[4:5], v[106:107]
	v_pk_mul_f32 v[14:15], v[14:15], v[98:99]
	v_pk_mul_f32 v[10:11], v[10:11], v[102:103]
	v_pk_mul_f32 v[6:7], v[6:7], v[108:109]
	v_pk_mul_f32 v[2:3], v[2:3], v[112:113]
	v_pk_mul_f32 v[0:1], v[0:1], v[110:111]
	v_pk_mul_f32 v[60:61], v[60:61], v[96:97]
	v_pk_mul_f32 v[56:57], v[56:57], v[100:101]
	v_pk_mul_f32 v[52:53], v[52:53], v[106:107]
	v_pk_mul_f32 v[62:63], v[62:63], v[98:99]
	v_pk_mul_f32 v[58:59], v[58:59], v[102:103]
	v_pk_mul_f32 v[54:55], v[54:55], v[108:109]
	v_pk_mul_f32 v[50:51], v[50:51], v[112:113]
	v_pk_mul_f32 v[48:49], v[48:49], v[110:111]
	v_pk_mul_f32 v[44:45], v[44:45], v[96:97]
	v_pk_mul_f32 v[40:41], v[40:41], v[100:101]
	v_pk_mul_f32 v[36:37], v[36:37], v[106:107]
	v_pk_mul_f32 v[46:47], v[46:47], v[98:99]
	v_pk_mul_f32 v[42:43], v[42:43], v[102:103]
	v_pk_mul_f32 v[38:39], v[38:39], v[108:109]
	v_pk_mul_f32 v[34:35], v[34:35], v[112:113]
	v_pk_mul_f32 v[32:33], v[32:33], v[110:111]
	v_pk_mul_f32 v[28:29], v[28:29], v[96:97]
	v_pk_mul_f32 v[24:25], v[24:25], v[100:101]
	v_pk_mul_f32 v[20:21], v[20:21], v[106:107]
	v_pk_mul_f32 v[30:31], v[30:31], v[98:99]
	v_pk_mul_f32 v[26:27], v[26:27], v[102:103]
	v_pk_mul_f32 v[22:23], v[22:23], v[108:109]
	v_pk_mul_f32 v[18:19], v[18:19], v[112:113]
	v_pk_mul_f32 v[16:17], v[16:17], v[110:111]
